# router phase: wave-0 shift-bias dot products with batched loads and level-wise wave sums
# speedup vs baseline: 1.0241x; 1.0003x over previous
.Lp5_ce_loop:
	v_lshl_add_u64 v[18:19], v[92:93], 0, s[50:51]
	s_mov_b64 s[52:53], 0x1000
	v_lshl_add_u64 v[188:189], v[18:19], 0, s[52:53]
	s_mov_b64 s[52:53], 0x2000
	v_lshl_add_u64 v[190:191], v[18:19], 0, s[52:53]
	s_mov_b64 s[52:53], 0x3000
	v_lshl_add_u64 v[244:245], v[18:19], 0, s[52:53]
	global_load_dword v180, v[2:3], off offset:-768
	global_load_dwordx4 v[148:151], v[18:19], off
	global_load_dwordx4 v[152:155], v[18:19], off offset:16
	global_load_dwordx4 v[156:159], v[18:19], off offset:32
	global_load_dwordx4 v[160:163], v[18:19], off offset:48
	global_load_dword v182, v[2:3], off offset:-512
	global_load_dwordx4 v[164:167], v[188:189], off
	global_load_dwordx4 v[168:171], v[188:189], off offset:16
	global_load_dwordx4 v[172:175], v[188:189], off offset:32
	global_load_dwordx4 v[176:179], v[188:189], off offset:48
	global_load_dword v184, v[2:3], off offset:-256
	global_load_dwordx4 v[196:199], v[190:191], off
	global_load_dwordx4 v[200:203], v[190:191], off offset:16
	global_load_dwordx4 v[204:207], v[190:191], off offset:32
	global_load_dwordx4 v[208:211], v[190:191], off offset:48
	global_load_dword v186, v[2:3], off
	global_load_dwordx4 v[212:215], v[244:245], off
	global_load_dwordx4 v[216:219], v[244:245], off offset:16
	global_load_dwordx4 v[220:223], v[244:245], off offset:32
	global_load_dwordx4 v[224:227], v[244:245], off offset:48
	s_add_u32 s50, s50, 0x4000
	s_addc_u32 s51, s51, 0
	v_lshl_add_u64 v[2:3], v[2:3], 0, s[46:47]
	s_waitcnt vmcnt(15)
	v_pk_fma_f32 v[16:17], v[180:181], v[148:149], v[16:17] op_sel_hi:[0,1,1]
	v_pk_fma_f32 v[14:15], v[180:181], v[150:151], v[14:15] op_sel_hi:[0,1,1]
	v_pk_fma_f32 v[12:13], v[180:181], v[152:153], v[12:13] op_sel_hi:[0,1,1]
	v_pk_fma_f32 v[10:11], v[180:181], v[154:155], v[10:11] op_sel_hi:[0,1,1]
	v_pk_fma_f32 v[8:9], v[180:181], v[156:157], v[8:9] op_sel_hi:[0,1,1]
	v_pk_fma_f32 v[6:7], v[180:181], v[158:159], v[6:7] op_sel_hi:[0,1,1]
	v_pk_fma_f32 v[4:5], v[180:181], v[160:161], v[4:5] op_sel_hi:[0,1,1]
	v_pk_fma_f32 v[0:1], v[180:181], v[162:163], v[0:1] op_sel_hi:[0,1,1]
	s_waitcnt vmcnt(10)
	v_pk_fma_f32 v[16:17], v[182:183], v[164:165], v[16:17] op_sel_hi:[0,1,1]
	v_pk_fma_f32 v[14:15], v[182:183], v[166:167], v[14:15] op_sel_hi:[0,1,1]
	v_pk_fma_f32 v[12:13], v[182:183], v[168:169], v[12:13] op_sel_hi:[0,1,1]
	v_pk_fma_f32 v[10:11], v[182:183], v[170:171], v[10:11] op_sel_hi:[0,1,1]
	v_pk_fma_f32 v[8:9], v[182:183], v[172:173], v[8:9] op_sel_hi:[0,1,1]
	v_pk_fma_f32 v[6:7], v[182:183], v[174:175], v[6:7] op_sel_hi:[0,1,1]
	v_pk_fma_f32 v[4:5], v[182:183], v[176:177], v[4:5] op_sel_hi:[0,1,1]
	v_pk_fma_f32 v[0:1], v[182:183], v[178:179], v[0:1] op_sel_hi:[0,1,1]
	s_waitcnt vmcnt(5)
	v_pk_fma_f32 v[16:17], v[184:185], v[196:197], v[16:17] op_sel_hi:[0,1,1]
	v_pk_fma_f32 v[14:15], v[184:185], v[198:199], v[14:15] op_sel_hi:[0,1,1]
	v_pk_fma_f32 v[12:13], v[184:185], v[200:201], v[12:13] op_sel_hi:[0,1,1]
	v_pk_fma_f32 v[10:11], v[184:185], v[202:203], v[10:11] op_sel_hi:[0,1,1]
	v_pk_fma_f32 v[8:9], v[184:185], v[204:205], v[8:9] op_sel_hi:[0,1,1]
	v_pk_fma_f32 v[6:7], v[184:185], v[206:207], v[6:7] op_sel_hi:[0,1,1]
	v_pk_fma_f32 v[4:5], v[184:185], v[208:209], v[4:5] op_sel_hi:[0,1,1]
	v_pk_fma_f32 v[0:1], v[184:185], v[210:211], v[0:1] op_sel_hi:[0,1,1]
	s_waitcnt vmcnt(0)
	v_pk_fma_f32 v[16:17], v[186:187], v[212:213], v[16:17] op_sel_hi:[0,1,1]
	v_pk_fma_f32 v[14:15], v[186:187], v[214:215], v[14:15] op_sel_hi:[0,1,1]
	v_pk_fma_f32 v[12:13], v[186:187], v[216:217], v[12:13] op_sel_hi:[0,1,1]
	v_pk_fma_f32 v[10:11], v[186:187], v[218:219], v[10:11] op_sel_hi:[0,1,1]
	v_pk_fma_f32 v[8:9], v[186:187], v[220:221], v[8:9] op_sel_hi:[0,1,1]
	v_pk_fma_f32 v[6:7], v[186:187], v[222:223], v[6:7] op_sel_hi:[0,1,1]
	v_pk_fma_f32 v[4:5], v[186:187], v[224:225], v[4:5] op_sel_hi:[0,1,1]
	v_pk_fma_f32 v[0:1], v[186:187], v[226:227], v[0:1] op_sel_hi:[0,1,1]
	s_cmp_eq_u32 s50, 0x10000
	s_cbranch_scc0 .Lp5_ce_loop
	v_xor_b32_e32 v228, 1, v133
	v_xor_b32_e32 v229, 2, v133
	v_xor_b32_e32 v230, 4, v133
	v_xor_b32_e32 v231, 8, v133
	v_xor_b32_e32 v232, 16, v133
	v_xor_b32_e32 v233, 32, v133
	v_lshlrev_b32_e32 v228, 2, v228
	v_lshlrev_b32_e32 v229, 2, v229
	v_lshlrev_b32_e32 v230, 2, v230
	v_lshlrev_b32_e32 v231, 2, v231
	v_lshlrev_b32_e32 v232, 2, v232
	v_lshlrev_b32_e32 v233, 2, v233
	ds_bpermute_b32 v234, v228, v16
	ds_bpermute_b32 v235, v228, v17
	ds_bpermute_b32 v236, v228, v14
	ds_bpermute_b32 v237, v228, v15
	ds_bpermute_b32 v238, v228, v12
	ds_bpermute_b32 v239, v228, v13
	ds_bpermute_b32 v240, v228, v10
	ds_bpermute_b32 v241, v228, v11
	s_waitcnt lgkmcnt(7)
	v_add_f32_e32 v16, v16, v234
	s_waitcnt lgkmcnt(6)
	v_add_f32_e32 v17, v17, v235
	s_waitcnt lgkmcnt(5)
	v_add_f32_e32 v14, v14, v236
	s_waitcnt lgkmcnt(4)
	v_add_f32_e32 v15, v15, v237
	s_waitcnt lgkmcnt(3)
	v_add_f32_e32 v12, v12, v238
	s_waitcnt lgkmcnt(2)
	v_add_f32_e32 v13, v13, v239
	s_waitcnt lgkmcnt(1)
	v_add_f32_e32 v10, v10, v240
	s_waitcnt lgkmcnt(0)
	v_add_f32_e32 v11, v11, v241
	ds_bpermute_b32 v234, v228, v8
	ds_bpermute_b32 v235, v228, v9
	ds_bpermute_b32 v236, v228, v6
	ds_bpermute_b32 v237, v228, v7
	ds_bpermute_b32 v238, v228, v4
	ds_bpermute_b32 v239, v228, v5
	ds_bpermute_b32 v240, v228, v0
	ds_bpermute_b32 v241, v228, v1
	s_waitcnt lgkmcnt(7)
	v_add_f32_e32 v8, v8, v234
	s_waitcnt lgkmcnt(6)
	v_add_f32_e32 v9, v9, v235
	s_waitcnt lgkmcnt(5)
	v_add_f32_e32 v6, v6, v236
	s_waitcnt lgkmcnt(4)
	v_add_f32_e32 v7, v7, v237
	s_waitcnt lgkmcnt(3)
	v_add_f32_e32 v4, v4, v238
	s_waitcnt lgkmcnt(2)
	v_add_f32_e32 v5, v5, v239
	s_waitcnt lgkmcnt(1)
	v_add_f32_e32 v0, v0, v240
	s_waitcnt lgkmcnt(0)
	v_add_f32_e32 v1, v1, v241
	ds_bpermute_b32 v234, v229, v16
	ds_bpermute_b32 v235, v229, v17
	ds_bpermute_b32 v236, v229, v14
	ds_bpermute_b32 v237, v229, v15
	ds_bpermute_b32 v238, v229, v12
	ds_bpermute_b32 v239, v229, v13
	ds_bpermute_b32 v240, v229, v10
	ds_bpermute_b32 v241, v229, v11
	s_waitcnt lgkmcnt(7)
	v_add_f32_e32 v16, v16, v234
	s_waitcnt lgkmcnt(6)
	v_add_f32_e32 v17, v17, v235
	s_waitcnt lgkmcnt(5)
	v_add_f32_e32 v14, v14, v236
	s_waitcnt lgkmcnt(4)
	v_add_f32_e32 v15, v15, v237
	s_waitcnt lgkmcnt(3)
	v_add_f32_e32 v12, v12, v238
	s_waitcnt lgkmcnt(2)
	v_add_f32_e32 v13, v13, v239
	s_waitcnt lgkmcnt(1)
	v_add_f32_e32 v10, v10, v240
	s_waitcnt lgkmcnt(0)
	v_add_f32_e32 v11, v11, v241
	ds_bpermute_b32 v234, v229, v8
	ds_bpermute_b32 v235, v229, v9
	ds_bpermute_b32 v236, v229, v6
	ds_bpermute_b32 v237, v229, v7
	ds_bpermute_b32 v238, v229, v4
	ds_bpermute_b32 v239, v229, v5
	ds_bpermute_b32 v240, v229, v0
	ds_bpermute_b32 v241, v229, v1
	s_waitcnt lgkmcnt(7)
	v_add_f32_e32 v8, v8, v234
	s_waitcnt lgkmcnt(6)
	v_add_f32_e32 v9, v9, v235
	s_waitcnt lgkmcnt(5)
	v_add_f32_e32 v6, v6, v236
	s_waitcnt lgkmcnt(4)
	v_add_f32_e32 v7, v7, v237
	s_waitcnt lgkmcnt(3)
	v_add_f32_e32 v4, v4, v238
	s_waitcnt lgkmcnt(2)
	v_add_f32_e32 v5, v5, v239
	s_waitcnt lgkmcnt(1)
	v_add_f32_e32 v0, v0, v240
	s_waitcnt lgkmcnt(0)
	v_add_f32_e32 v1, v1, v241
	ds_bpermute_b32 v234, v230, v16
	ds_bpermute_b32 v235, v230, v17
	ds_bpermute_b32 v236, v230, v14
	ds_bpermute_b32 v237, v230, v15
	ds_bpermute_b32 v238, v230, v12
	ds_bpermute_b32 v239, v230, v13
	ds_bpermute_b32 v240, v230, v10
	ds_bpermute_b32 v241, v230, v11
	s_waitcnt lgkmcnt(7)
	v_add_f32_e32 v16, v16, v234
	s_waitcnt lgkmcnt(6)
	v_add_f32_e32 v17, v17, v235
	s_waitcnt lgkmcnt(5)
	v_add_f32_e32 v14, v14, v236
	s_waitcnt lgkmcnt(4)
	v_add_f32_e32 v15, v15, v237
	s_waitcnt lgkmcnt(3)
	v_add_f32_e32 v12, v12, v238
	s_waitcnt lgkmcnt(2)
	v_add_f32_e32 v13, v13, v239
	s_waitcnt lgkmcnt(1)
	v_add_f32_e32 v10, v10, v240
	s_waitcnt lgkmcnt(0)
	v_add_f32_e32 v11, v11, v241
	ds_bpermute_b32 v234, v230, v8
	ds_bpermute_b32 v235, v230, v9
	ds_bpermute_b32 v236, v230, v6
	ds_bpermute_b32 v237, v230, v7
	ds_bpermute_b32 v238, v230, v4
	ds_bpermute_b32 v239, v230, v5
	ds_bpermute_b32 v240, v230, v0
	ds_bpermute_b32 v241, v230, v1
	s_waitcnt lgkmcnt(7)
	v_add_f32_e32 v8, v8, v234
	s_waitcnt lgkmcnt(6)
	v_add_f32_e32 v9, v9, v235
	s_waitcnt lgkmcnt(5)
	v_add_f32_e32 v6, v6, v236
	s_waitcnt lgkmcnt(4)
	v_add_f32_e32 v7, v7, v237
	s_waitcnt lgkmcnt(3)
	v_add_f32_e32 v4, v4, v238
	s_waitcnt lgkmcnt(2)
	v_add_f32_e32 v5, v5, v239
	s_waitcnt lgkmcnt(1)
	v_add_f32_e32 v0, v0, v240
	s_waitcnt lgkmcnt(0)
	v_add_f32_e32 v1, v1, v241
	ds_bpermute_b32 v234, v231, v16
	ds_bpermute_b32 v235, v231, v17
	ds_bpermute_b32 v236, v231, v14
	ds_bpermute_b32 v237, v231, v15
	ds_bpermute_b32 v238, v231, v12
	ds_bpermute_b32 v239, v231, v13
	ds_bpermute_b32 v240, v231, v10
	ds_bpermute_b32 v241, v231, v11
	s_waitcnt lgkmcnt(7)
	v_add_f32_e32 v16, v16, v234
	s_waitcnt lgkmcnt(6)
	v_add_f32_e32 v17, v17, v235
	s_waitcnt lgkmcnt(5)
	v_add_f32_e32 v14, v14, v236
	s_waitcnt lgkmcnt(4)
	v_add_f32_e32 v15, v15, v237
	s_waitcnt lgkmcnt(3)
	v_add_f32_e32 v12, v12, v238
	s_waitcnt lgkmcnt(2)
	v_add_f32_e32 v13, v13, v239
	s_waitcnt lgkmcnt(1)
	v_add_f32_e32 v10, v10, v240
	s_waitcnt lgkmcnt(0)
	v_add_f32_e32 v11, v11, v241
	ds_bpermute_b32 v234, v231, v8
	ds_bpermute_b32 v235, v231, v9
	ds_bpermute_b32 v236, v231, v6
	ds_bpermute_b32 v237, v231, v7
	ds_bpermute_b32 v238, v231, v4
	ds_bpermute_b32 v239, v231, v5
	ds_bpermute_b32 v240, v231, v0
	ds_bpermute_b32 v241, v231, v1
	s_waitcnt lgkmcnt(7)
	v_add_f32_e32 v8, v8, v234
	s_waitcnt lgkmcnt(6)
	v_add_f32_e32 v9, v9, v235
	s_waitcnt lgkmcnt(5)
	v_add_f32_e32 v6, v6, v236
	s_waitcnt lgkmcnt(4)
	v_add_f32_e32 v7, v7, v237
	s_waitcnt lgkmcnt(3)
	v_add_f32_e32 v4, v4, v238
	s_waitcnt lgkmcnt(2)
	v_add_f32_e32 v5, v5, v239
	s_waitcnt lgkmcnt(1)
	v_add_f32_e32 v0, v0, v240
	s_waitcnt lgkmcnt(0)
	v_add_f32_e32 v1, v1, v241
	ds_bpermute_b32 v234, v232, v16
	ds_bpermute_b32 v235, v232, v17
	ds_bpermute_b32 v236, v232, v14
	ds_bpermute_b32 v237, v232, v15
	ds_bpermute_b32 v238, v232, v12
	ds_bpermute_b32 v239, v232, v13
	ds_bpermute_b32 v240, v232, v10
	ds_bpermute_b32 v241, v232, v11
	s_waitcnt lgkmcnt(7)
	v_add_f32_e32 v16, v16, v234
	s_waitcnt lgkmcnt(6)
	v_add_f32_e32 v17, v17, v235
	s_waitcnt lgkmcnt(5)
	v_add_f32_e32 v14, v14, v236
	s_waitcnt lgkmcnt(4)
	v_add_f32_e32 v15, v15, v237
	s_waitcnt lgkmcnt(3)
	v_add_f32_e32 v12, v12, v238
	s_waitcnt lgkmcnt(2)
	v_add_f32_e32 v13, v13, v239
	s_waitcnt lgkmcnt(1)
	v_add_f32_e32 v10, v10, v240
	s_waitcnt lgkmcnt(0)
	v_add_f32_e32 v11, v11, v241
	ds_bpermute_b32 v234, v232, v8
	ds_bpermute_b32 v235, v232, v9
	ds_bpermute_b32 v236, v232, v6
	ds_bpermute_b32 v237, v232, v7
	ds_bpermute_b32 v238, v232, v4
	ds_bpermute_b32 v239, v232, v5
	ds_bpermute_b32 v240, v232, v0
	ds_bpermute_b32 v241, v232, v1
	s_waitcnt lgkmcnt(7)
	v_add_f32_e32 v8, v8, v234
	s_waitcnt lgkmcnt(6)
	v_add_f32_e32 v9, v9, v235
	s_waitcnt lgkmcnt(5)
	v_add_f32_e32 v6, v6, v236
	s_waitcnt lgkmcnt(4)
	v_add_f32_e32 v7, v7, v237
	s_waitcnt lgkmcnt(3)
	v_add_f32_e32 v4, v4, v238
	s_waitcnt lgkmcnt(2)
	v_add_f32_e32 v5, v5, v239
	s_waitcnt lgkmcnt(1)
	v_add_f32_e32 v0, v0, v240
	s_waitcnt lgkmcnt(0)
	v_add_f32_e32 v1, v1, v241
	ds_bpermute_b32 v234, v233, v16
	ds_bpermute_b32 v235, v233, v17
	ds_bpermute_b32 v236, v233, v14
	ds_bpermute_b32 v237, v233, v15
	ds_bpermute_b32 v238, v233, v12
	ds_bpermute_b32 v239, v233, v13
	ds_bpermute_b32 v240, v233, v10
	ds_bpermute_b32 v241, v233, v11
	s_waitcnt lgkmcnt(7)
	v_add_f32_e32 v16, v16, v234
	s_waitcnt lgkmcnt(6)
	v_add_f32_e32 v17, v17, v235
	s_waitcnt lgkmcnt(5)
	v_add_f32_e32 v14, v14, v236
	s_waitcnt lgkmcnt(4)
	v_add_f32_e32 v15, v15, v237
	s_waitcnt lgkmcnt(3)
	v_add_f32_e32 v12, v12, v238
	s_waitcnt lgkmcnt(2)
	v_add_f32_e32 v13, v13, v239
	s_waitcnt lgkmcnt(1)
	v_add_f32_e32 v10, v10, v240
	s_waitcnt lgkmcnt(0)
	v_add_f32_e32 v11, v11, v241
	ds_bpermute_b32 v234, v233, v8
	ds_bpermute_b32 v235, v233, v9
	ds_bpermute_b32 v236, v233, v6
	ds_bpermute_b32 v237, v233, v7
	ds_bpermute_b32 v238, v233, v4
	ds_bpermute_b32 v239, v233, v5
	ds_bpermute_b32 v240, v233, v0
	ds_bpermute_b32 v241, v233, v1
	s_waitcnt lgkmcnt(7)
	v_add_f32_e32 v8, v8, v234
	s_waitcnt lgkmcnt(6)
	v_add_f32_e32 v9, v9, v235
	s_waitcnt lgkmcnt(5)
	v_add_f32_e32 v6, v6, v236
	s_waitcnt lgkmcnt(4)
	v_add_f32_e32 v7, v7, v237
	s_waitcnt lgkmcnt(3)
	v_add_f32_e32 v4, v4, v238
	s_waitcnt lgkmcnt(2)
	v_add_f32_e32 v5, v5, v239
	s_waitcnt lgkmcnt(1)
	v_add_f32_e32 v0, v0, v240
	s_waitcnt lgkmcnt(0)
	v_add_f32_e32 v1, v1, v241
	s_and_saveexec_b64 s[50:51], s[2:3]
	v_mov_b32_e32 v234, s60
	ds_write_b32 v234, v16
	s_or_b64 exec, exec, s[50:51]
	s_and_saveexec_b64 s[50:51], s[4:5]
	v_mov_b32_e32 v234, s64
	ds_write_b32 v234, v17
	s_or_b64 exec, exec, s[50:51]
	s_and_saveexec_b64 s[50:51], s[6:7]
	v_mov_b32_e32 v234, s65
	ds_write_b32 v234, v14
	s_or_b64 exec, exec, s[50:51]
	s_and_saveexec_b64 s[50:51], s[8:9]
	v_mov_b32_e32 v234, s66
	ds_write_b32 v234, v15
	s_or_b64 exec, exec, s[50:51]
	s_and_saveexec_b64 s[50:51], s[10:11]
	v_mov_b32_e32 v234, s67
	ds_write_b32 v234, v12
	s_or_b64 exec, exec, s[50:51]
	s_and_saveexec_b64 s[50:51], s[12:13]
	v_mov_b32_e32 v234, s68
	ds_write_b32 v234, v13
	s_or_b64 exec, exec, s[50:51]
	s_and_saveexec_b64 s[50:51], s[14:15]
	v_mov_b32_e32 v234, s69
	ds_write_b32 v234, v10
	s_or_b64 exec, exec, s[50:51]
	s_and_saveexec_b64 s[50:51], s[16:17]
	v_mov_b32_e32 v234, s70
	ds_write_b32 v234, v11
	s_or_b64 exec, exec, s[50:51]
	s_and_saveexec_b64 s[50:51], s[18:19]
	v_mov_b32_e32 v234, s71
	ds_write_b32 v234, v8
	s_or_b64 exec, exec, s[50:51]
	s_and_saveexec_b64 s[50:51], s[20:21]
	v_mov_b32_e32 v234, s72
	ds_write_b32 v234, v9
	s_or_b64 exec, exec, s[50:51]
	s_and_saveexec_b64 s[50:51], s[22:23]
	v_mov_b32_e32 v234, s73
	ds_write_b32 v234, v6
	s_or_b64 exec, exec, s[50:51]
	s_and_saveexec_b64 s[50:51], s[24:25]
	v_mov_b32_e32 v234, s86
	ds_write_b32 v234, v7
	s_or_b64 exec, exec, s[50:51]
	s_and_saveexec_b64 s[50:51], s[26:27]
	v_mov_b32_e32 v234, s87
	ds_write_b32 v234, v4
	s_or_b64 exec, exec, s[50:51]
	s_and_saveexec_b64 s[50:51], s[28:29]
	v_mov_b32_e32 v234, s88
	ds_write_b32 v234, v5
	s_or_b64 exec, exec, s[50:51]
	s_and_saveexec_b64 s[50:51], s[30:31]
	v_mov_b32_e32 v234, s89
	ds_write_b32 v234, v0
	s_or_b64 exec, exec, s[50:51]
	s_and_saveexec_b64 s[50:51], s[34:35]
	v_mov_b32_e32 v234, s90
	ds_write_b32 v234, v1
	s_or_b64 exec, exec, s[50:51]
